# v1 plus: the per-row statistic publish store in the fused post-norm epilogue no longer waits for the outstanding residual loads (no register dependence)
# baseline (speedup 1.0000x reference)
.LBB0_493:
	s_or_b64 exec, exec, s[0:1]
	v_add_u32_e32 v114, s26, v213
	s_waitcnt lgkmcnt(0)
	s_barrier
	v_ashrrev_i32_e32 v115, 31, v114
	s_waitcnt lgkmcnt(0)
	v_lshlrev_b64 v[112:113], 5, v[114:115]
	v_lshl_add_u64 v[112:113], s[76:77], 0, v[112:113]
	v_add_u32_e32 v238, 0x20400, v235
	s_and_saveexec_b64 s[0:1], s[4:5]
	s_cbranch_execz .LBB0_495
	ds_read_b128 v[116:119], v238
	s_ashr_i32 s21, s20, 31
	s_waitcnt lgkmcnt(0)
	v_mov_b32_e32 v124, v117
	v_mov_b32_e32 v125, v118
	v_mov_b32_e32 v117, v119
	v_pk_add_f32 v[116:117], v[124:125], v[116:117]
	v_lshl_add_u64 v[118:119], s[20:21], 3, v[112:113]
	v_pk_add_f32 v[116:117], v[116:117], v[116:117] op_sel:[0,1] op_sel_hi:[1,0]
	s_nop 0
	v_mov_b32_e32 v117, s84
	flat_store_dwordx2 v[118:119], v[116:117] sc1

.LBB0_618:
	s_or_b64 exec, exec, s[0:1]
	v_add_u32_e32 v114, s21, v213
	s_waitcnt lgkmcnt(0)
	s_barrier
	v_ashrrev_i32_e32 v115, 31, v114
	s_waitcnt lgkmcnt(0)
	v_lshlrev_b64 v[112:113], 5, v[114:115]
	v_lshl_add_u64 v[112:113], s[76:77], 0, v[112:113]
	v_add_u32_e32 v238, 0x20400, v235
	s_and_saveexec_b64 s[0:1], s[4:5]
	s_cbranch_execz .LBB0_620
	ds_read_b128 v[116:119], v238
	s_ashr_i32 s19, s18, 31
	s_waitcnt lgkmcnt(0)
	v_mov_b32_e32 v124, v117
	v_mov_b32_e32 v125, v118
	v_mov_b32_e32 v117, v119
	v_pk_add_f32 v[116:117], v[124:125], v[116:117]
	v_lshl_add_u64 v[118:119], s[18:19], 3, v[112:113]
	v_pk_add_f32 v[116:117], v[116:117], v[116:117] op_sel:[0,1] op_sel_hi:[1,0]
	s_nop 0
	v_mov_b32_e32 v117, s84
	flat_store_dwordx2 v[118:119], v[116:117] sc1

.LBB0_801:
	s_or_b64 exec, exec, s[0:1]
	v_add_u32_e32 v114, s23, v214
	s_waitcnt lgkmcnt(0)
	s_barrier
	v_ashrrev_i32_e32 v115, 31, v114
	s_waitcnt lgkmcnt(0)
	v_lshlrev_b64 v[112:113], 5, v[114:115]
	v_lshl_add_u64 v[112:113], s[76:77], 0, v[112:113]
	s_and_saveexec_b64 s[0:1], s[4:5]
	s_cbranch_execz .LBB0_803
	v_add_u32_e32 v120, 0, v215
	v_add_u32_e32 v120, 0x20400, v120
	ds_read_b128 v[120:123], v120
	s_ashr_i32 s21, s20, 31
	s_waitcnt lgkmcnt(0)
	v_mov_b32_e32 v124, v121
	v_mov_b32_e32 v125, v122
	v_mov_b32_e32 v121, v123
	v_pk_add_f32 v[120:121], v[124:125], v[120:121]
	v_lshl_add_u64 v[122:123], s[20:21], 3, v[112:113]
	v_pk_add_f32 v[120:121], v[120:121], v[120:121] op_sel:[0,1] op_sel_hi:[1,0]
	s_nop 0
	v_mov_b32_e32 v121, s84
	flat_store_dwordx2 v[122:123], v[120:121] sc1
